# P7 epilogue hand-written (per-wave gate staging, no barriers), P1 epilogue fast path for plain tiles
# speedup vs baseline: 1.0831x; 1.0067x over previous
.LBB0_189:
	s_mul_hi_u32 s0, s34, 0xaaaaaaab
	s_lshr_b32 s12, s0, 2
	s_mul_i32 s0, s12, 6
	s_sub_i32 s0, s34, s0
	v_readlane_b32 s10, v246, 6
	s_add_i32 s13, s0, s10
	s_cmp_lt_u32 s13, 16
	s_cbranch_scc1 .Lp1e_ctx
	s_cmp_lt_u32 s12, 5
	s_cbranch_scc1 .Lp1e_slow
	s_branch .Lp1e_fast
.Lp1e_ctx:
	s_sub_i32 s0, s12, 4
	s_cmp_lt_u32 s0, 2
	s_cbranch_scc1 .Lp1e_slow
	s_sub_i32 s0, s12, 8
	s_cmp_lt_u32 s0, 4
	s_cbranch_scc1 .Lp1e_slow
.Lp1e_fast:
	s_nop 7
	s_nop 7
	s_mul_i32 s0, s13, 0x140000
	s_add_u32 s10, s18, s0
	s_addc_u32 s11, s19, 0
	s_lshl_b32 s0, s12, 8
	s_add_u32 s10, s10, s0
	s_addc_u32 s11, s11, 0
	v_lshl_add_u32 v178, v209, 2, v219
	v_mul_u32_u24_e32 v178, 0x1400, v178
	v_lshl_add_u32 v178, v208, 1, v178
	v_cvt_pk_bf16_f32 v180, v114, v82
	v_cvt_pk_bf16_f32 v181, v98, v66
	global_store_dwordx2 v178, v[180:181], s[10:11]
	s_add_u32 s10, s10, 0x1400
	s_addc_u32 s11, s11, 0
	v_cvt_pk_bf16_f32 v200, v115, v83
	v_cvt_pk_bf16_f32 v201, v99, v67
	global_store_dwordx2 v178, v[200:201], s[10:11]
	s_add_u32 s10, s10, 0x1400
	s_addc_u32 s11, s11, 0
	v_cvt_pk_bf16_f32 v202, v116, v84
	v_cvt_pk_bf16_f32 v203, v100, v68
	global_store_dwordx2 v178, v[202:203], s[10:11]
	s_add_u32 s10, s10, 0x1400
	s_addc_u32 s11, s11, 0
	v_cvt_pk_bf16_f32 v204, v117, v85
	v_cvt_pk_bf16_f32 v205, v101, v69
	global_store_dwordx2 v178, v[204:205], s[10:11]
	s_add_u32 s10, s10, 0x6400
	s_addc_u32 s11, s11, 0
	v_cvt_pk_bf16_f32 v180, v118, v86
	v_cvt_pk_bf16_f32 v181, v102, v70
	global_store_dwordx2 v178, v[180:181], s[10:11]
	s_add_u32 s10, s10, 0x1400
	s_addc_u32 s11, s11, 0
	v_cvt_pk_bf16_f32 v200, v119, v87
	v_cvt_pk_bf16_f32 v201, v103, v71
	global_store_dwordx2 v178, v[200:201], s[10:11]
	s_add_u32 s10, s10, 0x1400
	s_addc_u32 s11, s11, 0
	v_cvt_pk_bf16_f32 v202, v120, v88
	v_cvt_pk_bf16_f32 v203, v104, v72
	global_store_dwordx2 v178, v[202:203], s[10:11]
	s_add_u32 s10, s10, 0x1400
	s_addc_u32 s11, s11, 0
	v_cvt_pk_bf16_f32 v204, v121, v89
	v_cvt_pk_bf16_f32 v205, v105, v73
	global_store_dwordx2 v178, v[204:205], s[10:11]
	s_add_u32 s10, s10, 0x6400
	s_addc_u32 s11, s11, 0
	v_cvt_pk_bf16_f32 v180, v122, v90
	v_cvt_pk_bf16_f32 v181, v106, v74
	global_store_dwordx2 v178, v[180:181], s[10:11]
	s_add_u32 s10, s10, 0x1400
	s_addc_u32 s11, s11, 0
	v_cvt_pk_bf16_f32 v200, v123, v91
	v_cvt_pk_bf16_f32 v201, v107, v75
	global_store_dwordx2 v178, v[200:201], s[10:11]
	s_add_u32 s10, s10, 0x1400
	s_addc_u32 s11, s11, 0
	v_cvt_pk_bf16_f32 v202, v124, v92
	v_cvt_pk_bf16_f32 v203, v108, v76
	global_store_dwordx2 v178, v[202:203], s[10:11]
	s_add_u32 s10, s10, 0x1400
	s_addc_u32 s11, s11, 0
	v_cvt_pk_bf16_f32 v204, v125, v93
	v_cvt_pk_bf16_f32 v205, v109, v77
	global_store_dwordx2 v178, v[204:205], s[10:11]
	s_add_u32 s10, s10, 0x6400
	s_addc_u32 s11, s11, 0
	v_cvt_pk_bf16_f32 v180, v126, v94
	v_cvt_pk_bf16_f32 v181, v110, v78
	global_store_dwordx2 v178, v[180:181], s[10:11]
	s_add_u32 s10, s10, 0x1400
	s_addc_u32 s11, s11, 0
	v_cvt_pk_bf16_f32 v200, v127, v95
	v_cvt_pk_bf16_f32 v201, v111, v79
	global_store_dwordx2 v178, v[200:201], s[10:11]
	s_add_u32 s10, s10, 0x1400
	s_addc_u32 s11, s11, 0
	v_cvt_pk_bf16_f32 v202, v128, v96
	v_cvt_pk_bf16_f32 v203, v112, v80
	global_store_dwordx2 v178, v[202:203], s[10:11]
	s_add_u32 s10, s10, 0x1400
	s_addc_u32 s11, s11, 0
	v_cvt_pk_bf16_f32 v204, v129, v97
	v_cvt_pk_bf16_f32 v205, v113, v81
	global_store_dwordx2 v178, v[204:205], s[10:11]
	s_add_u32 s10, s10, 0x6400
	s_addc_u32 s11, s11, 0
	v_cvt_pk_bf16_f32 v180, v50, v18
	v_cvt_pk_bf16_f32 v181, v34, v2
	global_store_dwordx2 v178, v[180:181], s[10:11]
	s_add_u32 s10, s10, 0x1400
	s_addc_u32 s11, s11, 0
	v_cvt_pk_bf16_f32 v200, v51, v19
	v_cvt_pk_bf16_f32 v201, v35, v3
	global_store_dwordx2 v178, v[200:201], s[10:11]
	s_add_u32 s10, s10, 0x1400
	s_addc_u32 s11, s11, 0
	v_cvt_pk_bf16_f32 v202, v52, v20
	v_cvt_pk_bf16_f32 v203, v36, v4
	global_store_dwordx2 v178, v[202:203], s[10:11]
	s_add_u32 s10, s10, 0x1400
	s_addc_u32 s11, s11, 0
	v_cvt_pk_bf16_f32 v204, v53, v21
	v_cvt_pk_bf16_f32 v205, v37, v5
	global_store_dwordx2 v178, v[204:205], s[10:11]
	s_add_u32 s10, s10, 0x6400
	s_addc_u32 s11, s11, 0
	v_cvt_pk_bf16_f32 v180, v54, v22
	v_cvt_pk_bf16_f32 v181, v38, v6
	global_store_dwordx2 v178, v[180:181], s[10:11]
	s_add_u32 s10, s10, 0x1400
	s_addc_u32 s11, s11, 0
	v_cvt_pk_bf16_f32 v200, v55, v23
	v_cvt_pk_bf16_f32 v201, v39, v7
	global_store_dwordx2 v178, v[200:201], s[10:11]
	s_add_u32 s10, s10, 0x1400
	s_addc_u32 s11, s11, 0
	v_cvt_pk_bf16_f32 v202, v56, v24
	v_cvt_pk_bf16_f32 v203, v40, v8
	global_store_dwordx2 v178, v[202:203], s[10:11]
	s_add_u32 s10, s10, 0x1400
	s_addc_u32 s11, s11, 0
	v_cvt_pk_bf16_f32 v204, v57, v25
	v_cvt_pk_bf16_f32 v205, v41, v9
	global_store_dwordx2 v178, v[204:205], s[10:11]
	s_add_u32 s10, s10, 0x6400
	s_addc_u32 s11, s11, 0
	v_cvt_pk_bf16_f32 v180, v58, v26
	v_cvt_pk_bf16_f32 v181, v42, v10
	global_store_dwordx2 v178, v[180:181], s[10:11]
	s_add_u32 s10, s10, 0x1400
	s_addc_u32 s11, s11, 0
	v_cvt_pk_bf16_f32 v200, v59, v27
	v_cvt_pk_bf16_f32 v201, v43, v11
	global_store_dwordx2 v178, v[200:201], s[10:11]
	s_add_u32 s10, s10, 0x1400
	s_addc_u32 s11, s11, 0
	v_cvt_pk_bf16_f32 v202, v60, v28
	v_cvt_pk_bf16_f32 v203, v44, v12
	global_store_dwordx2 v178, v[202:203], s[10:11]
	s_add_u32 s10, s10, 0x1400
	s_addc_u32 s11, s11, 0
	v_cvt_pk_bf16_f32 v204, v61, v29
	v_cvt_pk_bf16_f32 v205, v45, v13
	global_store_dwordx2 v178, v[204:205], s[10:11]
	s_add_u32 s10, s10, 0x6400
	s_addc_u32 s11, s11, 0
	v_cvt_pk_bf16_f32 v180, v62, v30
	v_cvt_pk_bf16_f32 v181, v46, v14
	global_store_dwordx2 v178, v[180:181], s[10:11]
	s_add_u32 s10, s10, 0x1400
	s_addc_u32 s11, s11, 0
	v_cvt_pk_bf16_f32 v200, v63, v31
	v_cvt_pk_bf16_f32 v201, v47, v15
	global_store_dwordx2 v178, v[200:201], s[10:11]
	s_add_u32 s10, s10, 0x1400
	s_addc_u32 s11, s11, 0
	v_cvt_pk_bf16_f32 v202, v64, v32
	v_cvt_pk_bf16_f32 v203, v48, v16
	global_store_dwordx2 v178, v[202:203], s[10:11]
	s_add_u32 s10, s10, 0x1400
	s_addc_u32 s11, s11, 0
	v_cvt_pk_bf16_f32 v204, v65, v33
	v_cvt_pk_bf16_f32 v205, v49, v17
	global_store_dwordx2 v178, v[204:205], s[10:11]
	s_branch .LBB0_181
.Lp1e_slow:
	v_mov_b32_e32 v0, v209
	s_cmp_lt_u32 s13, 16
	s_cselect_b64 s[42:43], -1, 0
	s_cmp_gt_u32 s13, 15
	s_cselect_b64 s[10:11], -1, 0
	v_sub_co_u32_e64 v178, s[14:15], s34, 30
	v_lshlrev_b32_e32 v0, 2, v0
	v_add_u32_e32 v224, v0, v219
	s_and_b64 s[10:11], s[14:15], s[10:11]
	s_cmp_lg_u64 s[10:11], 0
	s_cbranch_scc0 .Lg1_norope
	s_barrier
	v_readlane_b32 s74, v247, 53
	v_readlane_b32 s75, v247, 54
	v_lshlrev_b32_e32 v174, 5, v187
	s_nop 4
	global_load_dwordx4 v[238:241], v174, s[74:75]
	global_load_dwordx4 v[170:173], v174, s[74:75] offset:16
	s_waitcnt vmcnt(0)
	ds_write_b128 v174, v[238:241] offset:57344
	ds_write_b128 v174, v[170:173] offset:57360
	s_waitcnt lgkmcnt(0)
	s_barrier

.LBB0_1417:
	s_nop 7
	s_nop 7
	s_add_i32 s0, s75, 0x2000
	v_and_b32_e32 v190, 0xfc, v204
	v_add_u32_e32 v190, s0, v190
	ds_write_b32 v190, v202
	v_lshl_add_u32 v218, v199, 4, s0
	s_add_i32 s0, s42, s43
	s_lshl_b32 s0, s0, 11
	s_add_u32 s10, s90, s0
	s_addc_u32 s11, s91, 0
	s_and_b32 s0, 0xffff, s40
	s_lshl_b32 s0, s0, 8
	s_add_u32 s10, s10, s0
	s_addc_u32 s11, s11, 0
	v_lshl_add_u32 v216, v199, 2, v203
	v_lshlrev_b32_e32 v216, 11, v216
	v_add_u32_e32 v216, v216, v0
	v_add_u32_e32 v217, 0x1000, v216
	ds_read_b128 v[230:233], v218
	ds_read_b128 v[234:237], v218 offset:32
	s_waitcnt lgkmcnt(1)
	v_mul_f32_e32 v114, v230, v114
	v_mul_f32_e32 v98, v230, v98
	v_mul_f32_e32 v82, v230, v82
	v_mul_f32_e32 v66, v230, v66
	v_mul_f32_e32 v115, v231, v115
	v_mul_f32_e32 v99, v231, v99
	v_mul_f32_e32 v83, v231, v83
	v_mul_f32_e32 v67, v231, v67
	v_mul_f32_e32 v116, v232, v116
	v_mul_f32_e32 v100, v232, v100
	v_mul_f32_e32 v84, v232, v84
	v_mul_f32_e32 v68, v232, v68
	v_mul_f32_e32 v117, v233, v117
	v_mul_f32_e32 v101, v233, v101
	v_mul_f32_e32 v85, v233, v85
	v_mul_f32_e32 v69, v233, v69
	v_cvt_pk_bf16_f32 v238, v114, v98
	v_cvt_pk_bf16_f32 v239, v82, v66
	v_cvt_pk_bf16_f32 v240, v115, v99
	v_cvt_pk_bf16_f32 v241, v83, v67
	v_cvt_pk_bf16_f32 v248, v116, v100
	v_cvt_pk_bf16_f32 v249, v84, v68
	v_cvt_pk_bf16_f32 v250, v117, v101
	v_cvt_pk_bf16_f32 v251, v85, v69
	global_store_dwordx2 v216, v[238:239], s[10:11]
	global_store_dwordx2 v216, v[240:241], s[10:11] offset:2048
	global_store_dwordx2 v217, v[248:249], s[10:11]
	global_store_dwordx2 v217, v[250:251], s[10:11] offset:2048
	s_add_u32 s10, s10, 0x4000
	s_addc_u32 s11, s11, 0
	ds_read_b128 v[230:233], v218 offset:64
	s_waitcnt lgkmcnt(1)
	v_mul_f32_e32 v118, v234, v118
	v_mul_f32_e32 v102, v234, v102
	v_mul_f32_e32 v86, v234, v86
	v_mul_f32_e32 v70, v234, v70
	v_mul_f32_e32 v119, v235, v119
	v_mul_f32_e32 v103, v235, v103
	v_mul_f32_e32 v87, v235, v87
	v_mul_f32_e32 v71, v235, v71
	v_mul_f32_e32 v120, v236, v120
	v_mul_f32_e32 v104, v236, v104
	v_mul_f32_e32 v88, v236, v88
	v_mul_f32_e32 v72, v236, v72
	v_mul_f32_e32 v121, v237, v121
	v_mul_f32_e32 v105, v237, v105
	v_mul_f32_e32 v89, v237, v89
	v_mul_f32_e32 v73, v237, v73
	v_cvt_pk_bf16_f32 v238, v118, v102
	v_cvt_pk_bf16_f32 v239, v86, v70
	v_cvt_pk_bf16_f32 v240, v119, v103
	v_cvt_pk_bf16_f32 v241, v87, v71
	v_cvt_pk_bf16_f32 v248, v120, v104
	v_cvt_pk_bf16_f32 v249, v88, v72
	v_cvt_pk_bf16_f32 v250, v121, v105
	v_cvt_pk_bf16_f32 v251, v89, v73
	global_store_dwordx2 v216, v[238:239], s[10:11]
	global_store_dwordx2 v216, v[240:241], s[10:11] offset:2048
	global_store_dwordx2 v217, v[248:249], s[10:11]
	global_store_dwordx2 v217, v[250:251], s[10:11] offset:2048
	s_add_u32 s10, s10, 0x4000
	s_addc_u32 s11, s11, 0
	ds_read_b128 v[234:237], v218 offset:96
	s_waitcnt lgkmcnt(1)
	v_mul_f32_e32 v122, v230, v122
	v_mul_f32_e32 v106, v230, v106
	v_mul_f32_e32 v90, v230, v90
	v_mul_f32_e32 v74, v230, v74
	v_mul_f32_e32 v123, v231, v123
	v_mul_f32_e32 v107, v231, v107
	v_mul_f32_e32 v91, v231, v91
	v_mul_f32_e32 v75, v231, v75
	v_mul_f32_e32 v124, v232, v124
	v_mul_f32_e32 v108, v232, v108
	v_mul_f32_e32 v92, v232, v92
	v_mul_f32_e32 v76, v232, v76
	v_mul_f32_e32 v125, v233, v125
	v_mul_f32_e32 v109, v233, v109
	v_mul_f32_e32 v93, v233, v93
	v_mul_f32_e32 v77, v233, v77
	v_cvt_pk_bf16_f32 v238, v122, v106
	v_cvt_pk_bf16_f32 v239, v90, v74
	v_cvt_pk_bf16_f32 v240, v123, v107
	v_cvt_pk_bf16_f32 v241, v91, v75
	v_cvt_pk_bf16_f32 v248, v124, v108
	v_cvt_pk_bf16_f32 v249, v92, v76
	v_cvt_pk_bf16_f32 v250, v125, v109
	v_cvt_pk_bf16_f32 v251, v93, v77
	global_store_dwordx2 v216, v[238:239], s[10:11]
	global_store_dwordx2 v216, v[240:241], s[10:11] offset:2048
	global_store_dwordx2 v217, v[248:249], s[10:11]
	global_store_dwordx2 v217, v[250:251], s[10:11] offset:2048
	s_add_u32 s10, s10, 0x4000
	s_addc_u32 s11, s11, 0
	ds_read_b128 v[230:233], v218 offset:128
	s_waitcnt lgkmcnt(1)
	v_mul_f32_e32 v126, v234, v126
	v_mul_f32_e32 v110, v234, v110
	v_mul_f32_e32 v94, v234, v94
	v_mul_f32_e32 v78, v234, v78
	v_mul_f32_e32 v127, v235, v127
	v_mul_f32_e32 v111, v235, v111
	v_mul_f32_e32 v95, v235, v95
	v_mul_f32_e32 v79, v235, v79
	v_mul_f32_e32 v128, v236, v128
	v_mul_f32_e32 v112, v236, v112
	v_mul_f32_e32 v96, v236, v96
	v_mul_f32_e32 v80, v236, v80
	v_mul_f32_e32 v129, v237, v129
	v_mul_f32_e32 v113, v237, v113
	v_mul_f32_e32 v97, v237, v97
	v_mul_f32_e32 v81, v237, v81
	v_cvt_pk_bf16_f32 v238, v126, v110
	v_cvt_pk_bf16_f32 v239, v94, v78
	v_cvt_pk_bf16_f32 v240, v127, v111
	v_cvt_pk_bf16_f32 v241, v95, v79
	v_cvt_pk_bf16_f32 v248, v128, v112
	v_cvt_pk_bf16_f32 v249, v96, v80
	v_cvt_pk_bf16_f32 v250, v129, v113
	v_cvt_pk_bf16_f32 v251, v97, v81
	global_store_dwordx2 v216, v[238:239], s[10:11]
	global_store_dwordx2 v216, v[240:241], s[10:11] offset:2048
	global_store_dwordx2 v217, v[248:249], s[10:11]
	global_store_dwordx2 v217, v[250:251], s[10:11] offset:2048
	s_add_u32 s10, s10, 0x4000
	s_addc_u32 s11, s11, 0
	ds_read_b128 v[234:237], v218 offset:160
	s_waitcnt lgkmcnt(1)
	v_mul_f32_e32 v50, v230, v50
	v_mul_f32_e32 v34, v230, v34
	v_mul_f32_e32 v18, v230, v18
	v_mul_f32_e32 v2, v230, v2
	v_mul_f32_e32 v51, v231, v51
	v_mul_f32_e32 v35, v231, v35
	v_mul_f32_e32 v19, v231, v19
	v_mul_f32_e32 v3, v231, v3
	v_mul_f32_e32 v52, v232, v52
	v_mul_f32_e32 v36, v232, v36
	v_mul_f32_e32 v20, v232, v20
	v_mul_f32_e32 v4, v232, v4
	v_mul_f32_e32 v53, v233, v53
	v_mul_f32_e32 v37, v233, v37
	v_mul_f32_e32 v21, v233, v21
	v_mul_f32_e32 v5, v233, v5
	v_cvt_pk_bf16_f32 v238, v50, v34
	v_cvt_pk_bf16_f32 v239, v18, v2
	v_cvt_pk_bf16_f32 v240, v51, v35
	v_cvt_pk_bf16_f32 v241, v19, v3
	v_cvt_pk_bf16_f32 v248, v52, v36
	v_cvt_pk_bf16_f32 v249, v20, v4
	v_cvt_pk_bf16_f32 v250, v53, v37
	v_cvt_pk_bf16_f32 v251, v21, v5
	global_store_dwordx2 v216, v[238:239], s[10:11]
	global_store_dwordx2 v216, v[240:241], s[10:11] offset:2048
	global_store_dwordx2 v217, v[248:249], s[10:11]
	global_store_dwordx2 v217, v[250:251], s[10:11] offset:2048
	s_add_u32 s10, s10, 0x4000
	s_addc_u32 s11, s11, 0
	ds_read_b128 v[230:233], v218 offset:192
	s_waitcnt lgkmcnt(1)
	v_mul_f32_e32 v54, v234, v54
	v_mul_f32_e32 v38, v234, v38
	v_mul_f32_e32 v22, v234, v22
	v_mul_f32_e32 v6, v234, v6
	v_mul_f32_e32 v55, v235, v55
	v_mul_f32_e32 v39, v235, v39
	v_mul_f32_e32 v23, v235, v23
	v_mul_f32_e32 v7, v235, v7
	v_mul_f32_e32 v56, v236, v56
	v_mul_f32_e32 v40, v236, v40
	v_mul_f32_e32 v24, v236, v24
	v_mul_f32_e32 v8, v236, v8
	v_mul_f32_e32 v57, v237, v57
	v_mul_f32_e32 v41, v237, v41
	v_mul_f32_e32 v25, v237, v25
	v_mul_f32_e32 v9, v237, v9
	v_cvt_pk_bf16_f32 v238, v54, v38
	v_cvt_pk_bf16_f32 v239, v22, v6
	v_cvt_pk_bf16_f32 v240, v55, v39
	v_cvt_pk_bf16_f32 v241, v23, v7
	v_cvt_pk_bf16_f32 v248, v56, v40
	v_cvt_pk_bf16_f32 v249, v24, v8
	v_cvt_pk_bf16_f32 v250, v57, v41
	v_cvt_pk_bf16_f32 v251, v25, v9
	global_store_dwordx2 v216, v[238:239], s[10:11]
	global_store_dwordx2 v216, v[240:241], s[10:11] offset:2048
	global_store_dwordx2 v217, v[248:249], s[10:11]
	global_store_dwordx2 v217, v[250:251], s[10:11] offset:2048
	s_add_u32 s10, s10, 0x4000
	s_addc_u32 s11, s11, 0
	ds_read_b128 v[234:237], v218 offset:224
	s_waitcnt lgkmcnt(1)
	v_mul_f32_e32 v58, v230, v58
	v_mul_f32_e32 v42, v230, v42
	v_mul_f32_e32 v26, v230, v26
	v_mul_f32_e32 v10, v230, v10
	v_mul_f32_e32 v59, v231, v59
	v_mul_f32_e32 v43, v231, v43
	v_mul_f32_e32 v27, v231, v27
	v_mul_f32_e32 v11, v231, v11
	v_mul_f32_e32 v60, v232, v60
	v_mul_f32_e32 v44, v232, v44
	v_mul_f32_e32 v28, v232, v28
	v_mul_f32_e32 v12, v232, v12
	v_mul_f32_e32 v61, v233, v61
	v_mul_f32_e32 v45, v233, v45
	v_mul_f32_e32 v29, v233, v29
	v_mul_f32_e32 v13, v233, v13
	v_cvt_pk_bf16_f32 v238, v58, v42
	v_cvt_pk_bf16_f32 v239, v26, v10
	v_cvt_pk_bf16_f32 v240, v59, v43
	v_cvt_pk_bf16_f32 v241, v27, v11
	v_cvt_pk_bf16_f32 v248, v60, v44
	v_cvt_pk_bf16_f32 v249, v28, v12
	v_cvt_pk_bf16_f32 v250, v61, v45
	v_cvt_pk_bf16_f32 v251, v29, v13
	global_store_dwordx2 v216, v[238:239], s[10:11]
	global_store_dwordx2 v216, v[240:241], s[10:11] offset:2048
	global_store_dwordx2 v217, v[248:249], s[10:11]
	global_store_dwordx2 v217, v[250:251], s[10:11] offset:2048
	s_add_u32 s10, s10, 0x4000
	s_addc_u32 s11, s11, 0
	s_waitcnt lgkmcnt(0)
	v_mul_f32_e32 v62, v234, v62
	v_mul_f32_e32 v46, v234, v46
	v_mul_f32_e32 v30, v234, v30
	v_mul_f32_e32 v14, v234, v14
	v_mul_f32_e32 v63, v235, v63
	v_mul_f32_e32 v47, v235, v47
	v_mul_f32_e32 v31, v235, v31
	v_mul_f32_e32 v15, v235, v15
	v_mul_f32_e32 v64, v236, v64
	v_mul_f32_e32 v48, v236, v48
	v_mul_f32_e32 v32, v236, v32
	v_mul_f32_e32 v16, v236, v16
	v_mul_f32_e32 v65, v237, v65
	v_mul_f32_e32 v49, v237, v49
	v_mul_f32_e32 v33, v237, v33
	v_mul_f32_e32 v17, v237, v17
	v_cvt_pk_bf16_f32 v238, v62, v46
	v_cvt_pk_bf16_f32 v239, v30, v14
	v_cvt_pk_bf16_f32 v240, v63, v47
	v_cvt_pk_bf16_f32 v241, v31, v15
	v_cvt_pk_bf16_f32 v248, v64, v48
	v_cvt_pk_bf16_f32 v249, v32, v16
	v_cvt_pk_bf16_f32 v250, v65, v49
	v_cvt_pk_bf16_f32 v251, v33, v17
	global_store_dwordx2 v216, v[238:239], s[10:11]
	global_store_dwordx2 v216, v[240:241], s[10:11] offset:2048
	global_store_dwordx2 v217, v[248:249], s[10:11]
	global_store_dwordx2 v217, v[250:251], s[10:11] offset:2048
	s_and_b64 vcc, exec, s[8:9]
	s_cbranch_vccnz .LBB0_1425
